# s29 with P1 column rotation 14 instead of 0
# speedup vs baseline: 1.0080x; 1.0080x over previous
.LBB0_103:
	s_cmp_lt_i32 s82, 2
	s_cselect_b64 s[4:5], -1, 0
	s_add_u32 s6, s80, 0x1100000
	v_writelane_b32 v255, s84, 25
	s_addc_u32 s7, s81, 0
	v_writelane_b32 v255, s6, 26
	s_nop 1
	v_writelane_b32 v255, s7, 27
	s_add_u32 s6, s80, 0x1300000
	s_addc_u32 s7, s81, 0
	v_writelane_b32 v255, s6, 28
	s_nop 1
	v_writelane_b32 v255, s7, 29
	s_add_u32 s6, s80, 0x1b00000
	s_addc_u32 s7, s81, 0
	s_add_u32 s69, s80, 0x2600000
	v_writelane_b32 v255, s6, 30
	s_addc_u32 s70, s81, 0
	s_nop 0
	v_writelane_b32 v255, s7, 31
	s_add_u32 s6, s80, 0x2c00000
	s_addc_u32 s7, s81, 0
	s_add_u32 s60, s80, 0x8c00000
	s_addc_u32 s61, s81, 0
	s_add_u32 s96, s80, 0xdc00000
	s_addc_u32 s91, s81, 0
	s_add_u32 s62, s80, 0x7c00000
	v_writelane_b32 v255, s6, 32
	s_addc_u32 s63, s81, 0
	s_and_b64 s[28:29], s[4:5], s[0:1]
	v_writelane_b32 v255, s7, 33
	s_andn2_b64 vcc, exec, s[28:29]
	s_cbranch_vccnz .LBB0_220
	s_cmpk_lt_i32 s2, 0x590
	s_cselect_b64 s[4:5], -1, 0
	s_cmpk_gt_i32 s2, 0x58f
	v_readfirstlane_b32 s6, v216
	s_cbranch_scc1 .LBB0_107
	s_cmpk_gt_i32 s2, 0x57f
	s_cbranch_scc1 .LBB0_108
	s_ashr_i32 s0, s2, 31
	s_lshr_b32 s0, s0, 29
	s_add_i32 s0, s2, s0
	s_ashr_i32 s1, s0, 3
	s_and_b32 s0, s0, -8
	s_sub_i32 s0, s2, s0
	s_cmp_lt_i32 s0, 0
	s_movk_i32 s7, 0xb1
	s_cselect_b32 s7, s7, 0xb0
	s_mul_i32 s0, s0, s7
	s_add_i32 s0, s0, s1
	s_mul_hi_i32 s1, s0, 0x2e8ba2e9
	s_lshr_b32 s7, s1, 31
	s_ashr_i32 s1, s1, 5
	s_add_i32 s1, s1, s7
	s_lshl_b32 s7, s1, 3
	s_mulk_i32 s1, 0xb0
	s_sub_i32 s0, s0, s1
	s_sext_i32_i16 s1, s0
	s_bfe_u32 s1, s1, 0x3001c
	s_add_i32 s1, s0, s1
	s_bfe_u32 s8, s1, 0xd0003
	s_and_b32 s1, s1, 0xfff8
	s_sub_i32 s0, s0, s1
	s_sext_i32_i16 s0, s0
	s_add_i32 s8, s8, 14
	s_add_i32 s38, s7, s0
	s_bfe_i32 s0, s8, 0x80000
	s_mul_i32 s0, s0, 0xffbb
	s_bfe_u32 s0, s0, 0x80008
	s_add_i32 s0, s0, s8
	s_bfe_i32 s1, s0, 0x80000
	s_and_b32 s1, 0xffff, s1
	s_lshr_b32 s1, s1, 4
	s_bfe_u32 s0, s0, 0x10007
	s_add_i32 s0, s1, s0
	s_mul_i32 s0, s0, 22
	s_sub_i32 s0, s8, s0
	s_mov_b32 s59, 0
	s_sext_i32_i8 s90, s0
	s_mov_b64 s[0:1], -1
	s_andn2_b64 vcc, exec, s[4:5]
	v_lshlrev_b32_e32 v16, 2, v216
	s_cbranch_vccz .LBB0_109
	s_branch .LBB0_178

.LBB0_117:
	s_andn2_b64 vcc, exec, s[12:13]
	s_mov_b32 s69, 1
	s_cbranch_vccnz .LBB0_119
	s_ashr_i32 s5, s4, 31
	s_lshr_b32 s5, s5, 29
	s_add_i32 s5, s4, s5
	s_ashr_i32 s12, s5, 3
	s_and_b32 s5, s5, -8
	s_sub_i32 s4, s4, s5
	s_cmp_lt_i32 s4, 0
	s_movk_i32 s5, 0xb1
	s_cselect_b32 s5, s5, 0xb0
	s_mul_i32 s4, s4, s5
	s_add_i32 s4, s4, s12
	s_mul_hi_i32 s5, s4, 0x2e8ba2e9
	s_lshr_b32 s12, s5, 31
	s_ashr_i32 s5, s5, 5
	s_add_i32 s5, s5, s12
	s_lshl_b32 s12, s5, 3
	s_sub_i32 s13, 64, s12
	s_min_i32 s13, s13, 8
	s_abs_i32 s14, s13
	v_cvt_f32_u32_e32 v0, s14
	s_sub_i32 s16, 0, s14
	s_mulk_i32 s5, 0xb0
	s_sub_i32 s4, s4, s5
	v_rcp_iflag_f32_e32 v0, v0
	s_abs_i32 s5, s4
	s_xor_b32 s15, s4, s13
	s_ashr_i32 s15, s15, 31
	v_mul_f32_e32 v0, 0x4f7ffffe, v0
	v_cvt_u32_f32_e32 v0, v0
	s_mov_b32 s69, 0
	v_readfirstlane_b32 s17, v0
	s_mul_i32 s16, s16, s17
	s_mul_hi_u32 s16, s17, s16
	s_add_i32 s17, s17, s16
	s_mul_hi_u32 s16, s5, s17
	s_mul_i32 s17, s16, s14
	s_sub_i32 s5, s5, s17
	s_add_i32 s17, s16, 1
	s_sub_i32 s18, s5, s14
	s_cmp_ge_u32 s5, s14
	s_cselect_b32 s16, s17, s16
	s_cselect_b32 s5, s18, s5
	s_add_i32 s17, s16, 1
	s_cmp_ge_u32 s5, s14
	s_cselect_b32 s5, s17, s16
	s_xor_b32 s5, s5, s15
	s_sub_i32 s5, s5, s15
	s_mul_i32 s13, s5, s13
	s_sub_i32 s4, s4, s13
	s_add_i32 s5, s5, 14
	s_add_i32 s42, s12, s4
	s_sext_i32_i16 s4, s5
	s_mulk_i32 s4, 0xba3
	s_lshr_b32 s12, s4, 31
	s_lshr_b32 s4, s4, 16
	s_add_i32 s4, s4, s12
	s_mul_i32 s4, s4, 22
	s_sub_i32 s4, s5, s4
	s_sext_i32_i16 s44, s4
